# sel fast path on raw QK scores, exp/cvt in MFMA gaps, 4 independent row-sum accumulators, in-place P pack
# baseline (speedup 1.0000x reference)
; __device__ __forceinline__ int crow(int r, int hi) { return (r & 3) + 8 * (r >> 2) + 4 * hi; }
; template <bool WITH_O>
; __device__ __forceinline__ void softmax_step(float& m, float& l, f32x16 (&o)[4], f32x16& p0, f32x16& p1, LAS float* wsf, int r32, int hi) {
;     float mxa = fmaxf(fmaxf(p0[0], p1[0]), p0[1]), mxb = fmaxf(fmaxf(p1[1], p0[2]), p1[2]);
; #pragma unroll
;     for (int r = 3; r < 15; r += 2) { mxa = fmaxf(fmaxf(mxa, p0[r]), p1[r]); mxb = fmaxf(fmaxf(mxb, p0[r + 1]), p1[r + 1]); }
;     float mx = fmaxf(fmaxf(mxa, mxb), fmaxf(p0[15], p1[15]));
;     mx = fmaxf(mx, __shfl_xor(mx, 32));
;     const bool grow = __any(mx > m + 8.f);
;     const float mnew = grow ? fmaxf(m, mx) : m;
;     const float f = grow ? __builtin_amdgcn_exp2f(m - mnew) : 1.f;
;     m = mnew;
;     float s = 0.f;
; #pragma unroll
;     for (int r = 0; r < 16; ++r) { p0[r] = __builtin_amdgcn_exp2f(p0[r] - mnew); p1[r] = __builtin_amdgcn_exp2f(p1[r] - mnew); s += p0[r] + p1[r]; }
;     l = l * f + s;
;     if (WITH_O) {
;         if (grow) {
;             if (hi == 0) wsf[r32] = f;
;             asm volatile("s_waitcnt lgkmcnt(0)" ::: "memory");
; #pragma unroll
;             for (int r = 0; r < 16; ++r) { const float fr = wsf[crow(r, hi)];
; #pragma unroll
;                 for (int db = 0; db < 4; ++db) o[db][r] *= fr; }
; __device__ __forceinline__ void nsa_unit(int hk, int T, LAS unsigned char* lds, LAS float* wsf, const AttnPtrs& P) {
;     ...
;                 const unsigned mw = sel[(8 * w + qi) * 8 + (j >> 5)];
;                 const bool mine = (mw >> (j & 31)) & 1u;
; #pragma unroll
;                 for (int r = 0; r < 16; ++r) { const int key = 64 * j + crow(r, hi);
;                     if (!mine || key > tq) p0[r] = -INFINITY; if (!mine || key + 32 > tq) p1[r] = -INFINITY; }
;                 softmax_step<true>(m, l, o, p0, p1, wsf, r32, hi);
.LBB0_1458:
	s_lshr_b32 s6, s11, 5
	s_lshl_b32 s8, 1, s11
	v_readlane_b32 s9, v253, s6
	s_and_b32 s9, s9, s8
	s_cmp_eq_u32 s9, 0
	s_cbranch_scc1 .LBB0_1464
	s_mul_i32 s7, s7, 0x8c00
	s_add_i32 s12, s7, 0
	v_add3_u32 v0, s12, v195, v166
	v_lshl_add_u32 v254, s6, 2, v196
	ds_read_b32 v254, v254
	ds_read_b128 v[2:5], v0
	ds_read_b128 v[6:9], v0 offset:32
	ds_read_b128 v[10:13], v0 offset:8704
	ds_read_b128 v[202:205], v0 offset:8736
	s_waitcnt lgkmcnt(3)
	v_mfma_f32_32x32x16_bf16 v[96:111], v[2:5], v[112:115], 0
	ds_read_b128 v[2:5], v0 offset:64
	ds_read_b128 v[206:209], v0 offset:8768
	s_waitcnt lgkmcnt(3)
	v_mfma_f32_32x32x16_bf16 v[64:79], v[10:13], v[112:115], 0
	v_mfma_f32_32x32x16_bf16 v[96:111], v[6:9], v[116:119], v[96:111]
	ds_read_b128 v[6:9], v0 offset:96
	ds_read_b128 v[10:13], v0 offset:8800
	s_waitcnt lgkmcnt(4)
	v_mfma_f32_32x32x16_bf16 v[64:79], v[202:205], v[116:119], v[64:79]
	s_waitcnt lgkmcnt(3)
	v_mfma_f32_32x32x16_bf16 v[96:111], v[2:5], v[120:123], v[96:111]
	ds_read_b128 v[2:5], v0 offset:128
	ds_read_b128 v[202:205], v0 offset:8832
	s_waitcnt lgkmcnt(4)
	v_mfma_f32_32x32x16_bf16 v[64:79], v[206:209], v[120:123], v[64:79]
	s_waitcnt lgkmcnt(3)
	v_mfma_f32_32x32x16_bf16 v[96:111], v[6:9], v[124:127], v[96:111]
	ds_read_b128 v[6:9], v0 offset:160
	ds_read_b128 v[206:209], v0 offset:8864
	s_waitcnt lgkmcnt(4)
	v_mfma_f32_32x32x16_bf16 v[64:79], v[10:13], v[124:127], v[64:79]
	s_waitcnt lgkmcnt(3)
	v_mfma_f32_32x32x16_bf16 v[96:111], v[2:5], v[128:131], v[96:111]
	ds_read_b128 v[2:5], v0 offset:192
	ds_read_b128 v[10:13], v0 offset:8896
	s_waitcnt lgkmcnt(4)
	v_mfma_f32_32x32x16_bf16 v[64:79], v[202:205], v[128:131], v[64:79]
	s_waitcnt lgkmcnt(3)
	v_mfma_f32_32x32x16_bf16 v[96:111], v[6:9], v[132:135], v[96:111]
	ds_read_b128 v[6:9], v0 offset:224
	ds_read_b128 v[202:205], v0 offset:8928
	s_waitcnt lgkmcnt(4)
	v_mfma_f32_32x32x16_bf16 v[64:79], v[206:209], v[132:135], v[64:79]
	s_waitcnt lgkmcnt(3)
	v_mfma_f32_32x32x16_bf16 v[96:111], v[2:5], v[136:139], v[96:111]
	s_waitcnt lgkmcnt(2)
	v_mfma_f32_32x32x16_bf16 v[64:79], v[10:13], v[136:139], v[64:79]
	s_waitcnt lgkmcnt(1)
	v_mfma_f32_32x32x16_bf16 v[96:111], v[6:9], v[140:143], v[96:111]
	s_waitcnt lgkmcnt(0)
	v_mfma_f32_32x32x16_bf16 v[64:79], v[202:205], v[140:143], v[64:79]
	v_and_b32_e32 v0, s8, v254
	v_cmp_eq_u32_e32 vcc, 0, v0
	s_cmp_eq_u32 s11, s97
	s_cbranch_scc1 .Lsel_lastmask
	s_mov_b64 s[8:9], vcc
	s_nop 6
	v_max3_f32 v2, v96, v64, v97
	v_max3_f32 v3, v65, v98, v66
	v_max3_f32 v2, v2, v99, v67
	v_max3_f32 v3, v3, v100, v68
	v_max3_f32 v2, v2, v101, v69
	v_max3_f32 v3, v3, v102, v70
	v_max3_f32 v2, v2, v103, v71
	v_max3_f32 v3, v3, v104, v72
	v_max3_f32 v2, v2, v105, v73
	v_max3_f32 v3, v3, v106, v74
	v_max3_f32 v2, v2, v107, v75
	v_max3_f32 v3, v3, v108, v76
	v_max3_f32 v2, v2, v109, v77
	v_max3_f32 v3, v3, v110, v78
	v_max3_f32 v2, v2, v111, v79
	v_max_f32_e32 v2, v2, v3
	v_cndmask_b32_e64 v2, v2, v185, s[8:9]
	v_mov_b32_e32 v3, v2
	s_nop 1
	v_permlane32_swap_b32_e32 v3, v2
	v_max_f32_e32 v2, v2, v3
	v_add_f32_e32 v3, 0x41000000, v200
	v_cmp_gt_f32_e32 vcc, v2, v3
	s_cmp_eq_u64 vcc, 0
	v_max_f32_e32 v3, v200, v200
	v_max_f32_e32 v0, v3, v2
	s_cselect_b64 s[6:7], -1, 0
	v_cndmask_b32_e64 v0, v0, v200, s[6:7]
	v_sub_f32_e32 v14, v200, v0
	v_exp_f32_e32 v14, v14
	v_mov_b32_e32 v15, 0x7f800000
	v_cndmask_b32_e64 v15, v0, v15, s[8:9]
	s_and_b64 vcc, exec, s[6:7]
	s_cbranch_vccnz .Lsel_f_nogrow
	s_and_saveexec_b64 s[8:9], s[4:5]
	ds_write_b32 v192, v14
	s_or_b64 exec, exec, s[8:9]
	s_waitcnt lgkmcnt(0)
	ds_read_b128 v[2:5], v193 offset:96
	ds_read_b128 v[6:9], v193 offset:64
	ds_read_b128 v[10:13], v193 offset:32
	ds_read_b128 v[202:205], v193
	s_waitcnt lgkmcnt(3)
	v_pk_mul_f32 v[60:61], v[60:61], v[2:3]
	s_waitcnt lgkmcnt(2)
	v_pk_mul_f32 v[56:57], v[56:57], v[6:7]
	s_waitcnt lgkmcnt(1)
	v_pk_mul_f32 v[52:53], v[52:53], v[10:11]
	v_pk_mul_f32 v[62:63], v[62:63], v[4:5]
	v_pk_mul_f32 v[58:59], v[58:59], v[8:9]
	v_pk_mul_f32 v[54:55], v[54:55], v[12:13]
	s_waitcnt lgkmcnt(0)
	v_pk_mul_f32 v[50:51], v[50:51], v[204:205]
	v_pk_mul_f32 v[48:49], v[48:49], v[202:203]
	v_pk_mul_f32 v[44:45], v[44:45], v[2:3]
	v_pk_mul_f32 v[40:41], v[40:41], v[6:7]
	v_pk_mul_f32 v[36:37], v[36:37], v[10:11]
	v_pk_mul_f32 v[46:47], v[46:47], v[4:5]
	v_pk_mul_f32 v[42:43], v[42:43], v[8:9]
	v_pk_mul_f32 v[38:39], v[38:39], v[12:13]
	v_pk_mul_f32 v[34:35], v[34:35], v[204:205]
	v_pk_mul_f32 v[32:33], v[32:33], v[202:203]
	v_pk_mul_f32 v[28:29], v[28:29], v[2:3]
	v_pk_mul_f32 v[24:25], v[24:25], v[6:7]
	v_pk_mul_f32 v[20:21], v[20:21], v[10:11]
	v_pk_mul_f32 v[30:31], v[30:31], v[4:5]
	v_pk_mul_f32 v[26:27], v[26:27], v[8:9]
	v_pk_mul_f32 v[22:23], v[22:23], v[12:13]
	v_pk_mul_f32 v[18:19], v[18:19], v[204:205]
	v_pk_mul_f32 v[16:17], v[16:17], v[202:203]
	v_pk_mul_f32 v[92:93], v[92:93], v[2:3]
	v_pk_mul_f32 v[88:89], v[88:89], v[6:7]
	v_pk_mul_f32 v[84:85], v[84:85], v[10:11]
	v_pk_mul_f32 v[94:95], v[94:95], v[4:5]
	v_pk_mul_f32 v[90:91], v[90:91], v[8:9]
	v_pk_mul_f32 v[86:87], v[86:87], v[12:13]
	v_pk_mul_f32 v[82:83], v[82:83], v[204:205]
	v_pk_mul_f32 v[80:81], v[80:81], v[202:203]
; #define LAS __attribute__((address_space(3)))
; __device__ __forceinline__ unsigned pk2(float lo, float hi) { f32x2 v = {lo, hi}; bf16x2_t b = __builtin_convertvector(v, bf16x2_t); return __builtin_bit_cast(unsigned, b); }
; #define PV_LD(i_) do { vf[(i_) & 3] = *(const LAS bf16x8*)(vb2 + ((i_) & 3) * 32 * VRS + ((i_) >> 2) * 32); } while (0)
; __device__ __forceinline__ void pv_tile(f32x16 (&o)[4], const f32x16& p0, const f32x16& p1, const LAS unsigned char* Vt, int r32, int hi) {
;     bf16x8 pa[4];
; #pragma unroll
;     for (int s = 0; s < 4; ++s) { const int b = 8 * (s & 1); u32x4 w;
;         if (s < 2) { w.x = pk2(p0[b], p0[b + 1]); w.y = pk2(p0[b + 2], p0[b + 3]); w.z = pk2(p0[b + 4], p0[b + 5]); w.w = pk2(p0[b + 6], p0[b + 7]); }
;         else { w.x = pk2(p1[b], p1[b + 1]); w.y = pk2(p1[b + 2], p1[b + 3]); w.z = pk2(p1[b + 4], p1[b + 5]); w.w = pk2(p1[b + 6], p1[b + 7]); }
;         pa[s] = __builtin_bit_cast(bf16x8, w); }
;     const LAS unsigned char* vb2 = Vt + r32 * VRS + hi * 16;
;     bf16x8 vf[4];
;     ...
;     PV_LD(0); PV_LD(1); PV_LD(2);
;     __builtin_amdgcn_sched_barrier(0);
; #pragma unroll
;     for (int i = 0; i < 16; ++i) {
;         if (i + 3 < 16) PV_LD(i + 3);
;         o[i & 3] = __builtin_amdgcn_mfma_f32_32x32x16_bf16(pa[i >> 2], vf[i & 3], o[i & 3], 0, 0, 0);
;         __builtin_amdgcn_sched_barrier(0);
;     }
; template <bool WITH_O>
; __device__ __forceinline__ void softmax_step(float& m, float& l, f32x16 (&o)[4], f32x16& p0, f32x16& p1, LAS float* wsf, int r32, int hi) {
;     ...
;     for (int r = 0; r < 16; ++r) { p0[r] = __builtin_amdgcn_exp2f(p0[r] - mnew); p1[r] = __builtin_amdgcn_exp2f(p1[r] - mnew); s += p0[r] + p1[r]; }
;     l = l * f + s;
.Lsel_f_nogrow:
	v_add3_u32 v201, s12, v198, v166
	ds_read_b128 v[2:5], v201 offset:17408
	ds_read_b128 v[6:9], v201 offset:22016
	ds_read_b128 v[10:13], v201 offset:26624
	v_sub_f32_e32 v96, v96, v15
	v_sub_f32_e32 v97, v97, v15
	v_exp_f32_e32 v96, v96
	v_exp_f32_e32 v97, v97
	v_sub_f32_e32 v98, v98, v15
	v_sub_f32_e32 v99, v99, v15
	v_exp_f32_e32 v98, v98
	v_exp_f32_e32 v99, v99
	v_sub_f32_e32 v100, v100, v15
	v_sub_f32_e32 v101, v101, v15
	v_exp_f32_e32 v100, v100
	v_exp_f32_e32 v101, v101
	v_sub_f32_e32 v102, v102, v15
	v_sub_f32_e32 v103, v103, v15
	v_exp_f32_e32 v102, v102
	v_exp_f32_e32 v103, v103
	v_add_f32_e32 v200, v96, v100
	v_add_f32_e32 v202, v97, v101
	v_add_f32_e32 v203, v98, v102
	v_add_f32_e32 v204, v99, v103
	v_cvt_pk_bf16_f32 v96, v96, v97
	v_cvt_pk_bf16_f32 v97, v98, v99
	v_cvt_pk_bf16_f32 v98, v100, v101
	v_cvt_pk_bf16_f32 v99, v102, v103
	s_nop 1
	s_waitcnt lgkmcnt(2)
	v_mfma_f32_32x32x16_bf16 v[48:63], v[96:99], v[2:5], v[48:63]
	ds_read_b128 v[2:5], v201 offset:31232
	v_sub_f32_e32 v104, v104, v15
	v_sub_f32_e32 v105, v105, v15
	v_exp_f32_e32 v104, v104
	v_exp_f32_e32 v105, v105
	v_sub_f32_e32 v106, v106, v15
	v_sub_f32_e32 v107, v107, v15
	v_exp_f32_e32 v106, v106
	s_waitcnt lgkmcnt(2)
	v_mfma_f32_32x32x16_bf16 v[32:47], v[96:99], v[6:9], v[32:47]
	ds_read_b128 v[6:9], v201 offset:17440
	v_exp_f32_e32 v107, v107
	v_sub_f32_e32 v108, v108, v15
	v_sub_f32_e32 v109, v109, v15
	v_exp_f32_e32 v108, v108
	v_exp_f32_e32 v109, v109
	v_sub_f32_e32 v110, v110, v15
	v_sub_f32_e32 v111, v111, v15
	s_waitcnt lgkmcnt(2)
	v_mfma_f32_32x32x16_bf16 v[16:31], v[96:99], v[10:13], v[16:31]
	ds_read_b128 v[10:13], v201 offset:22048
	v_exp_f32_e32 v110, v110
	v_exp_f32_e32 v111, v111
	v_add_f32_e32 v200, v200, v104
	v_add_f32_e32 v202, v202, v105
	v_add_f32_e32 v203, v203, v106
	v_add_f32_e32 v204, v204, v107
	v_add_f32_e32 v200, v200, v108
	s_waitcnt lgkmcnt(2)
	v_mfma_f32_32x32x16_bf16 v[80:95], v[96:99], v[2:5], v[80:95]
	ds_read_b128 v[2:5], v201 offset:26656
	v_add_f32_e32 v202, v202, v109
	v_add_f32_e32 v203, v203, v110
	v_add_f32_e32 v204, v204, v111
	v_cvt_pk_bf16_f32 v104, v104, v105
	v_cvt_pk_bf16_f32 v105, v106, v107
	v_cvt_pk_bf16_f32 v106, v108, v109
	v_cvt_pk_bf16_f32 v107, v110, v111
	s_nop 1
	s_waitcnt lgkmcnt(2)
	v_mfma_f32_32x32x16_bf16 v[48:63], v[104:107], v[6:9], v[48:63]
	ds_read_b128 v[6:9], v201 offset:31264
	v_sub_f32_e32 v64, v64, v15
	v_sub_f32_e32 v65, v65, v15
	v_exp_f32_e32 v64, v64
	v_exp_f32_e32 v65, v65
	v_sub_f32_e32 v66, v66, v15
	v_sub_f32_e32 v67, v67, v15
	v_exp_f32_e32 v66, v66
	s_waitcnt lgkmcnt(2)
	v_mfma_f32_32x32x16_bf16 v[32:47], v[104:107], v[10:13], v[32:47]
	ds_read_b128 v[10:13], v201 offset:17472
	v_exp_f32_e32 v67, v67
	v_sub_f32_e32 v68, v68, v15
	v_sub_f32_e32 v69, v69, v15
	v_exp_f32_e32 v68, v68
	v_exp_f32_e32 v69, v69
	v_sub_f32_e32 v70, v70, v15
	v_sub_f32_e32 v71, v71, v15
	s_waitcnt lgkmcnt(2)
	v_mfma_f32_32x32x16_bf16 v[16:31], v[104:107], v[2:5], v[16:31]
	ds_read_b128 v[2:5], v201 offset:22080
	v_exp_f32_e32 v70, v70
	v_exp_f32_e32 v71, v71
	v_add_f32_e32 v200, v200, v64
	v_add_f32_e32 v202, v202, v65
	v_add_f32_e32 v203, v203, v66
	v_add_f32_e32 v204, v204, v67
	v_add_f32_e32 v200, v200, v68
	s_waitcnt lgkmcnt(2)
	v_mfma_f32_32x32x16_bf16 v[80:95], v[104:107], v[6:9], v[80:95]
	ds_read_b128 v[6:9], v201 offset:26688
	v_add_f32_e32 v202, v202, v69
	v_add_f32_e32 v203, v203, v70
	v_add_f32_e32 v204, v204, v71
	v_cvt_pk_bf16_f32 v64, v64, v65
	v_cvt_pk_bf16_f32 v65, v66, v67
	v_cvt_pk_bf16_f32 v66, v68, v69
	v_cvt_pk_bf16_f32 v67, v70, v71
	s_nop 1
	s_waitcnt lgkmcnt(2)
	v_mfma_f32_32x32x16_bf16 v[48:63], v[64:67], v[10:13], v[48:63]
	ds_read_b128 v[10:13], v201 offset:31296
	v_sub_f32_e32 v72, v72, v15
	v_sub_f32_e32 v73, v73, v15
	v_exp_f32_e32 v72, v72
	v_exp_f32_e32 v73, v73
	v_sub_f32_e32 v74, v74, v15
	v_sub_f32_e32 v75, v75, v15
	v_exp_f32_e32 v74, v74
	s_waitcnt lgkmcnt(2)
	v_mfma_f32_32x32x16_bf16 v[32:47], v[64:67], v[2:5], v[32:47]
	ds_read_b128 v[2:5], v201 offset:17504
	v_exp_f32_e32 v75, v75
	v_sub_f32_e32 v76, v76, v15
	v_sub_f32_e32 v77, v77, v15
	v_exp_f32_e32 v76, v76
	v_exp_f32_e32 v77, v77
	v_sub_f32_e32 v78, v78, v15
	v_sub_f32_e32 v79, v79, v15
	s_waitcnt lgkmcnt(2)
	v_mfma_f32_32x32x16_bf16 v[16:31], v[64:67], v[6:9], v[16:31]
	ds_read_b128 v[6:9], v201 offset:22112
	v_exp_f32_e32 v78, v78
	v_exp_f32_e32 v79, v79
	v_add_f32_e32 v200, v200, v72
	v_add_f32_e32 v202, v202, v73
	v_add_f32_e32 v203, v203, v74
	v_add_f32_e32 v204, v204, v75
	v_add_f32_e32 v200, v200, v76
	s_waitcnt lgkmcnt(2)
	v_mfma_f32_32x32x16_bf16 v[80:95], v[64:67], v[10:13], v[80:95]
	ds_read_b128 v[10:13], v201 offset:26720
	v_add_f32_e32 v202, v202, v77
	v_add_f32_e32 v203, v203, v78
	v_add_f32_e32 v204, v204, v79
	v_cvt_pk_bf16_f32 v72, v72, v73
	v_cvt_pk_bf16_f32 v73, v74, v75
	v_cvt_pk_bf16_f32 v74, v76, v77
	v_cvt_pk_bf16_f32 v75, v78, v79
	s_nop 1
	s_waitcnt lgkmcnt(2)
	v_mfma_f32_32x32x16_bf16 v[48:63], v[72:75], v[2:5], v[48:63]
	ds_read_b128 v[2:5], v201 offset:31328
	s_waitcnt lgkmcnt(2)
	v_mfma_f32_32x32x16_bf16 v[32:47], v[72:75], v[6:9], v[32:47]
	s_waitcnt lgkmcnt(1)
	v_mfma_f32_32x32x16_bf16 v[16:31], v[72:75], v[10:13], v[16:31]
	s_waitcnt lgkmcnt(0)
	v_mfma_f32_32x32x16_bf16 v[80:95], v[72:75], v[2:5], v[80:95]
	v_add_f32_e32 v200, v200, v202
	v_add_f32_e32 v203, v203, v204
	v_cndmask_b32_e64 v201, v14, 1.0, s[6:7]
	v_add_f32_e32 v200, v200, v203
	v_fmac_f32_e32 v200, v199, v201
	v_mov_b32_e32 v199, v200
	s_branch .LBB0_1465
